# P4 compressed/selected attention loops: P*V fragment LDS reads run 2-3 fragments ahead of the MFMAs with counted lgkmcnt waits (probability registers reused as fragment buffers)
# baseline (speedup 1.0000x reference)
; #define MFMA32(a, b, c) __builtin_amdgcn_mfma_f32_32x32x16_bf16((a), (b), (c), 0, 0, 0)
; DI unsigned pack2(float a, float b) { fv2 v = {a, b}; return __builtin_bit_cast(unsigned, __builtin_convertvector(v, bfv2)); }
; template <int MODE> ...
;     ...
; #pragma unroll
;     for (int kt = 0; kt < 2; ++kt)
; #pragma unroll
;       for (int sp = 0; sp < 2; ++sp) {
;         const bf16x8 fb = __builtin_bit_cast(bf16x8, make_uint4(pack2(s[kt][8 * sp + 0], s[kt][8 * sp + 1]), pack2(s[kt][8 * sp + 2], s[kt][8 * sp + 3]),
;                                                                pack2(s[kt][8 * sp + 4], s[kt][8 * sp + 5]), pack2(s[kt][8 * sp + 6], s[kt][8 * sp + 7])));
; #pragma unroll
;         for (int dt = 0; dt < 2; ++dt) {
;           const bf16_t* vr = Vs + (32 * dt + r31) * LDT + 32 * kt + 16 * sp + 4 * h;
;           const uint2 lo = *(const uint2*)vr; const uint2 hi = *(const uint2*)(vr + 8);
;           const bf16x8 fa = __builtin_bit_cast(bf16x8, make_uint4(lo.x, lo.y, hi.x, hi.y));
;           o[dt] = MFMA32(fa, fb, o[dt]);
;         }
;       }
.LBB0_535:
	v_add_u32_e32 v0, 0x2000, v152
	ds_read_b128 v[4:7], v0 offset:1024
	v_cvt_pk_bf16_f32 v8, v64, v65
	v_cvt_pk_bf16_f32 v9, v66, v67
	v_cvt_pk_bf16_f32 v10, v68, v69
	v_cvt_pk_bf16_f32 v11, v70, v71
	v_add_u32_e32 v3, 0x3000, v152
	s_add_i32 s8, s8, 1
	s_add_i32 s2, s2, 64
	s_andn2_b64 vcc, exec, s[4:5]
	s_waitcnt lgkmcnt(0)
	v_mfma_f32_32x32x16_bf16 v[32:47], v[4:7], v[8:11], v[32:47]
	ds_read_b128 v[4:7], v3 offset:1536
	s_waitcnt lgkmcnt(0)
	v_mfma_f32_32x32x16_bf16 v[48:63], v[4:7], v[8:11], v[48:63]
	ds_read_b128 v[4:7], v0 offset:1056
	v_cvt_pk_bf16_f32 v8, v72, v73
	v_cvt_pk_bf16_f32 v9, v74, v75
	v_cvt_pk_bf16_f32 v10, v76, v77
	v_cvt_pk_bf16_f32 v11, v78, v79
	ds_read_b128 v[72:75], v3 offset:1568
	ds_read_b128 v[76:79], v0 offset:1088
	s_waitcnt lgkmcnt(2)
	s_nop 0
	v_mfma_f32_32x32x16_bf16 v[32:47], v[4:7], v[8:11], v[32:47]
	ds_read_b128 v[4:7], v3 offset:1600
	s_waitcnt lgkmcnt(2)
	v_mfma_f32_32x32x16_bf16 v[48:63], v[72:75], v[8:11], v[48:63]
	ds_read_b128 v[72:75], v0 offset:1120
	v_cvt_pk_bf16_f32 v8, v80, v81
	v_cvt_pk_bf16_f32 v9, v82, v83
	v_cvt_pk_bf16_f32 v10, v84, v85
	v_cvt_pk_bf16_f32 v11, v86, v87
	s_waitcnt lgkmcnt(2)
	s_nop 0
	v_mfma_f32_32x32x16_bf16 v[32:47], v[76:79], v[8:11], v[32:47]
	ds_read_b128 v[76:79], v3 offset:1632
	s_waitcnt lgkmcnt(2)
	v_mfma_f32_32x32x16_bf16 v[48:63], v[4:7], v[8:11], v[48:63]
	v_cvt_pk_bf16_f32 v8, v88, v89
	v_cvt_pk_bf16_f32 v9, v90, v91
	v_cvt_pk_bf16_f32 v10, v92, v93
	v_cvt_pk_bf16_f32 v11, v94, v95
	s_waitcnt lgkmcnt(1)
	s_nop 0
	v_mfma_f32_32x32x16_bf16 v[32:47], v[72:75], v[8:11], v[32:47]
	s_waitcnt lgkmcnt(0)
	v_mfma_f32_32x32x16_bf16 v[48:63], v[76:79], v[8:11], v[48:63]
	s_cbranch_vccz .LBB0_538
	v_mov_b32_e32 v80, v2
	s_branch .LBB0_523

; #define MFMA32(a, b, c) __builtin_amdgcn_mfma_f32_32x32x16_bf16((a), (b), (c), 0, 0, 0)
; DI unsigned pack2(float a, float b) { fv2 v = {a, b}; return __builtin_bit_cast(unsigned, __builtin_convertvector(v, bfv2)); }
; template <int MODE> ...
;     ...
; #pragma unroll
;     for (int kt = 0; kt < 2; ++kt)
; #pragma unroll
;       for (int sp = 0; sp < 2; ++sp) {
;         const bf16x8 fb = __builtin_bit_cast(bf16x8, make_uint4(pack2(s[kt][8 * sp + 0], s[kt][8 * sp + 1]), pack2(s[kt][8 * sp + 2], s[kt][8 * sp + 3]),
;                                                                pack2(s[kt][8 * sp + 4], s[kt][8 * sp + 5]), pack2(s[kt][8 * sp + 6], s[kt][8 * sp + 7])));
; #pragma unroll
;         for (int dt = 0; dt < 2; ++dt) {
;           const bf16_t* vr = Vs + (32 * dt + r31) * LDT + 32 * kt + 16 * sp + 4 * h;
;           const uint2 lo = *(const uint2*)vr; const uint2 hi = *(const uint2*)(vr + 8);
;           const bf16x8 fa = __builtin_bit_cast(bf16x8, make_uint4(lo.x, lo.y, hi.x, hi.y));
;           o[dt] = MFMA32(fa, fb, o[dt]);
;         }
;       }
.LBB0_658:
	v_add_u32_e32 v0, 0x2000, v138
	v_add_u32_e32 v70, 0x3000, v138
	ds_read_b128 v[66:69], v0 offset:1024
	v_cvt_pk_bf16_f32 v34, v34, v35
	v_cvt_pk_bf16_f32 v35, v36, v37
	v_cvt_pk_bf16_f32 v36, v38, v39
	v_cvt_pk_bf16_f32 v37, v40, v41
	ds_read_b128 v[38:41], v70 offset:1536
	s_add_i32 s20, s20, 1
	s_add_i32 s2, s2, 64
	s_waitcnt lgkmcnt(1)
	v_mfma_f32_32x32x16_bf16 v[2:17], v[66:69], v[34:37], v[2:17]
	s_andn2_b64 vcc, exec, s[4:5]
	s_waitcnt lgkmcnt(0)
	v_mfma_f32_32x32x16_bf16 v[18:33], v[38:41], v[34:37], v[18:33]
	ds_read_b128 v[34:37], v0 offset:1056
	v_cvt_pk_bf16_f32 v38, v42, v43
	v_cvt_pk_bf16_f32 v39, v44, v45
	v_cvt_pk_bf16_f32 v40, v46, v47
	v_cvt_pk_bf16_f32 v41, v48, v49
	ds_read_b128 v[42:45], v70 offset:1568
	ds_read_b128 v[46:49], v0 offset:1088
	s_waitcnt lgkmcnt(2)
	s_nop 0
	v_mfma_f32_32x32x16_bf16 v[2:17], v[34:37], v[38:41], v[2:17]
	ds_read_b128 v[34:37], v70 offset:1600
	s_waitcnt lgkmcnt(2)
	v_mfma_f32_32x32x16_bf16 v[18:33], v[42:45], v[38:41], v[18:33]
	ds_read_b128 v[42:45], v0 offset:1120
	v_cvt_pk_bf16_f32 v38, v50, v51
	v_cvt_pk_bf16_f32 v39, v52, v53
	v_cvt_pk_bf16_f32 v40, v54, v55
	v_cvt_pk_bf16_f32 v41, v56, v57
	s_waitcnt lgkmcnt(2)
	s_nop 0
	v_mfma_f32_32x32x16_bf16 v[2:17], v[46:49], v[38:41], v[2:17]
	ds_read_b128 v[46:49], v70 offset:1632
	s_waitcnt lgkmcnt(2)
	v_mfma_f32_32x32x16_bf16 v[18:33], v[34:37], v[38:41], v[18:33]
	v_cvt_pk_bf16_f32 v38, v58, v59
	v_cvt_pk_bf16_f32 v39, v60, v61
	v_cvt_pk_bf16_f32 v40, v62, v63
	v_cvt_pk_bf16_f32 v41, v64, v65
	s_waitcnt lgkmcnt(1)
	s_nop 0
	v_mfma_f32_32x32x16_bf16 v[2:17], v[42:45], v[38:41], v[2:17]
	s_waitcnt lgkmcnt(0)
	v_mfma_f32_32x32x16_bf16 v[18:33], v[46:49], v[38:41], v[18:33]
	s_cbranch_vccz .LBB0_757
	v_mov_b32_e32 v66, v139
	s_branch .LBB0_646
